# MLA attention loop: softmax scale-subtract done with 8 v_pk_fma_f32 and row sum with v_pk_add_f32 (packed f32 VALU) instead of 16 fma + 16 add
# speedup vs baseline: 1.0101x; 1.0010x over previous
; __device__ __forceinline__ unsigned cvt_pk_bf16(float lo, float hi) { unsigned r; asm volatile("v_cvt_pk_bf16_f32 %0, %1, %2" : "=v"(r) : "v"(lo), "v"(hi)); return r; }
; __device__ __forceinline__ float fast_exp2(float x) { return __builtin_amdgcn_exp2f(x); }
; template <int DQ, int TYPE>
; __device__ __forceinline__ void attn_item(PP p, int layer, int b, int h, int qt, char* lds, const int tid_, unsigned* next_ctr, volatile XLAS unsigned* slot) {
;     ...
;             float ls = 0.f;
; #pragma unroll
;             for (int i = 0; i < 16; ++i) { sacc[i] = fast_exp2(__builtin_fmaf(sacc[i], c, -mnew)); ls += sacc[i]; }
;             l_run = l_run * alpha + ls;
;             if (__builtin_amdgcn_ballot_w64(mx > m_old_) != 0) {
; #pragma unroll
;                 for (int md = 0; md < 4; ++md) O[md] *= alpha;
;             }
; #pragma unroll
;             for (int s2 = 0; s2 < 2; ++s2) {
;                 if (s2 == 0) {
; #pragma unroll
;                     for (int md = 0; md < 4; ++md) { vf[1][md][0] = *(const u32x2*)(vb0 + 16 + md * 32 * VLD); vf[1][md][1] = *(const u32x2*)(vb0 + 16 + md * 32 * VLD + 8); }
;                 }
;                 u32x4 pb;
;                 pb.x = cvt_pk_bf16(sacc[8 * s2 + 0], sacc[8 * s2 + 1]); pb.y = cvt_pk_bf16(sacc[8 * s2 + 2], sacc[8 * s2 + 3]);
;                 pb.z = cvt_pk_bf16(sacc[8 * s2 + 4], sacc[8 * s2 + 5]); pb.w = cvt_pk_bf16(sacc[8 * s2 + 6], sacc[8 * s2 + 7]);
;                 const bf16x8 bfrag = __builtin_bit_cast(bf16x8, pb);
;                 __builtin_amdgcn_sched_barrier(0);
; #pragma unroll
;                 for (int md = 0; md < 4; ++md) {
;                     u32x4 av; av.x = vf[s2][md][0].x; av.y = vf[s2][md][0].y; av.z = vf[s2][md][1].x; av.w = vf[s2][md][1].y;
;                     O[md] = __builtin_amdgcn_mfma_f32_32x32x16_bf16(__builtin_bit_cast(bf16x8, av), bfrag, O[md], 0, 0, 0);
;                 }
;                 __builtin_amdgcn_sched_barrier(0);
;             }
.LBB0_669:
	v_pk_fma_f32 v[244:245], v[66:67], s[86:87], v[200:201] op_sel_hi:[1,0,0] neg_lo:[0,0,1] neg_hi:[0,0,1]
	v_exp_f32_e32 v205, v244
	v_exp_f32_e32 v206, v245
	v_pk_fma_f32 v[244:245], v[68:69], s[86:87], v[200:201] op_sel_hi:[1,0,0] neg_lo:[0,0,1] neg_hi:[0,0,1]
	v_exp_f32_e32 v207, v244
	v_exp_f32_e32 v208, v245
	v_pk_fma_f32 v[244:245], v[70:71], s[86:87], v[200:201] op_sel_hi:[1,0,0] neg_lo:[0,0,1] neg_hi:[0,0,1]
	v_exp_f32_e32 v209, v244
	v_exp_f32_e32 v210, v245
	v_pk_fma_f32 v[244:245], v[72:73], s[86:87], v[200:201] op_sel_hi:[1,0,0] neg_lo:[0,0,1] neg_hi:[0,0,1]
	v_exp_f32_e32 v211, v244
	v_exp_f32_e32 v212, v245
	v_pk_fma_f32 v[244:245], v[74:75], s[86:87], v[200:201] op_sel_hi:[1,0,0] neg_lo:[0,0,1] neg_hi:[0,0,1]
	v_exp_f32_e32 v213, v244
	v_exp_f32_e32 v214, v245
	v_pk_fma_f32 v[244:245], v[76:77], s[86:87], v[200:201] op_sel_hi:[1,0,0] neg_lo:[0,0,1] neg_hi:[0,0,1]
	v_exp_f32_e32 v215, v244
	v_exp_f32_e32 v216, v245
	v_pk_fma_f32 v[244:245], v[78:79], s[86:87], v[200:201] op_sel_hi:[1,0,0] neg_lo:[0,0,1] neg_hi:[0,0,1]
	v_exp_f32_e32 v217, v244
	v_exp_f32_e32 v218, v245
	v_pk_fma_f32 v[244:245], v[80:81], s[86:87], v[200:201] op_sel_hi:[1,0,0] neg_lo:[0,0,1] neg_hi:[0,0,1]
	v_exp_f32_e32 v219, v244
	v_exp_f32_e32 v230, v245
	v_pk_add_f32 v[246:247], v[206:207], v[208:209]
	v_pk_add_f32 v[246:247], v[210:211], v[246:247]
	v_pk_add_f32 v[246:247], v[212:213], v[246:247]
	v_pk_add_f32 v[246:247], v[214:215], v[246:247]
	v_pk_add_f32 v[246:247], v[216:217], v[246:247]
	v_pk_add_f32 v[246:247], v[218:219], v[246:247]
	v_add_f32_e32 v246, v246, v247
	v_add_f32_e32 v246, v205, v246
	v_add_f32_e32 v231, v230, v246
	ds_read2_b64 v[66:69], v203 offset0:132 offset1:134
	ds_read2_b64 v[70:73], v201 offset0:164 offset1:166
	ds_read2_b64 v[74:77], v204 offset0:196 offset1:198
	ds_read2_b64 v[78:81], v202 offset0:228 offset1:230
	v_fmac_f32_e32 v231, v199, v192
	v_cvt_pk_bf16_f32 v202, v205, v206
	v_cvt_pk_bf16_f32 v203, v207, v208
	v_cvt_pk_bf16_f32 v204, v209, v210
	v_cvt_pk_bf16_f32 v205, v211, v212
	s_waitcnt lgkmcnt(4)
	s_nop 0
	v_mfma_f32_32x32x16_bf16 v[18:33], v[162:165], v[202:205], v[18:33]
	v_mfma_f32_32x32x16_bf16 v[2:17], v[158:161], v[202:205], v[2:17]
	v_mfma_f32_32x32x16_bf16 v[50:65], v[154:157], v[202:205], v[50:65]
	v_mfma_f32_32x32x16_bf16 v[34:49], v[150:153], v[202:205], v[34:49]
	v_cvt_pk_bf16_f32 v150, v213, v214
	v_cvt_pk_bf16_f32 v151, v215, v216
	v_cvt_pk_bf16_f32 v152, v217, v218
	v_cvt_pk_bf16_f32 v153, v219, v230
	s_waitcnt lgkmcnt(3)
	v_mfma_f32_32x32x16_bf16 v[18:33], v[66:69], v[150:153], v[18:33]
	s_waitcnt lgkmcnt(2)
	v_mfma_f32_32x32x16_bf16 v[2:17], v[70:73], v[150:153], v[2:17]
	s_waitcnt lgkmcnt(1)
	v_mfma_f32_32x32x16_bf16 v[50:65], v[74:77], v[150:153], v[50:65]
	s_waitcnt lgkmcnt(0)
	v_mfma_f32_32x32x16_bf16 v[34:49], v[78:81], v[150:153], v[34:49]
	v_mov_b32_e32 v199, v231
	s_andn2_b64 vcc, exec, s[12:13]
	s_cbranch_vccz .LBB0_671
	s_branch .LBB0_672
